# HGRN2 loader waves: per-step load address arithmetic hoisted out of the loop (SGPR base + fixed lane offsets), on top of the GLA hoist and loader priority
# speedup vs baseline: 1.0185x; 1.0012x over previous
.LBB0_1017:
	s_or_b64 exec, exec, s[4:5]
	s_waitcnt lgkmcnt(0)
	s_barrier
	s_mov_b32 s6, 0
	v_lshlrev_b32_e32 v212, 3, v158
	v_and_b32_e32 v213, 0x78, v212
	v_ashrrev_i32_e32 v214, 4, v158
	v_add_u32_e32 v215, 0x100, v158
	v_ashrrev_i32_e32 v216, 4, v215
	v_add_u32_e32 v217, 0x200, v158
	v_lshrrev_b32_e32 v217, 4, v217
	v_add_u32_e32 v218, 0x300, v158
	v_lshrrev_b32_e32 v218, 4, v218
	v_mul_lo_u32 v219, v214, s60
	v_mul_lo_u32 v220, v216, s60
	v_mul_lo_u32 v221, v217, s60
	v_mul_lo_u32 v222, v218, s60
	v_or_b32_e32 v223, s12, v213
	v_add_u32_e32 v200, v223, v219
	v_add_u32_e32 v201, v220, v223
	v_add_u32_e32 v202, v221, v223
	v_add_u32_e32 v203, v222, v223
	v_and_or_b32 v223, v212, 56, s17
	v_lshrrev_b32_e32 v224, 3, v158
	v_mul_lo_u32 v224, v224, s60
	v_add_u32_e32 v204, v224, v223
	v_lshrrev_b32_e32 v224, 3, v215
	v_mul_lo_u32 v224, v224, s60
	v_add_u32_e32 v205, v224, v223
	v_or_b32_e32 v223, s13, v213
	v_add_u32_e32 v206, v223, v219
	v_add_u32_e32 v207, v220, v223
	v_add_u32_e32 v208, v221, v223
	v_add_u32_e32 v209, v222, v223
	v_or_b32_e32 v223, s16, v213
	v_add_u32_e32 v224, s20, v214
	v_mul_lo_u32 v224, v224, s60
	v_add_u32_e32 v210, v224, v223
	v_add_u32_e32 v224, s20, v216
	v_mul_lo_u32 v224, v224, s60
	v_add_u32_e32 v211, v224, v223
	v_lshlrev_b32_e32 v200, 1, v200
	v_lshlrev_b32_e32 v201, 1, v201
	v_lshlrev_b32_e32 v202, 1, v202
	v_lshlrev_b32_e32 v203, 1, v203
	v_lshlrev_b32_e32 v204, 1, v204
	v_lshlrev_b32_e32 v205, 1, v205
	v_lshlrev_b32_e32 v206, 1, v206
	v_lshlrev_b32_e32 v207, 1, v207
	v_lshlrev_b32_e32 v208, 1, v208
	v_lshlrev_b32_e32 v209, 1, v209
	v_lshlrev_b32_e32 v210, 1, v210
	v_lshlrev_b32_e32 v211, 1, v211
	s_setprio 3
	s_branch .LBB0_1020

.LBB0_1020:
	v_mov_b32_e32 v159, v158
	s_mov_b32 s0, 0xffffffe
	v_add_u32_e32 v162, 0x100, v159
	v_add_u32_e32 v164, 0x200, v159
	v_add_u32_e32 v166, 0x300, v159
	v_ashrrev_i32_e32 v169, 3, v159
	v_ashrrev_i32_e32 v170, 3, v162
	v_lshrrev_b32_e32 v163, 4, v162
	v_lshrrev_b32_e32 v165, 4, v164
	v_lshrrev_b32_e32 v167, 4, v166
	v_bfe_u32 v162, v159, 3, 1
	v_lshrrev_b32_e32 v164, 3, v164
	v_lshrrev_b32_e32 v166, 3, v166
	v_add_u32_e32 v173, s2, v169
	v_add_u32_e32 v174, s2, v170
	v_and_or_b32 v171, v169, s0, v162
	v_and_or_b32 v172, v170, s0, v162
	v_and_or_b32 v164, v164, s0, v162
	v_and_or_b32 v166, v166, s0, v162
	v_and_or_b32 v173, v173, s0, v162
	v_and_or_b32 v174, v174, s0, v162
	s_andn2_b32 s0, 1, s6
	v_lshlrev_b32_e32 v16, 4, v159
	v_lshrrev_b32_e32 v161, 4, v159
	s_mul_i32 s0, s0, 0x10400
	v_and_b32_e32 v160, 0xf0, v16
	v_mul_lo_u32 v161, v161, s25
	s_add_i32 s7, s0, 0
	v_mul_lo_u32 v163, v163, s25
	v_add3_u32 v161, s7, v161, v160
	v_mul_lo_u32 v165, v165, s25
	v_mul_lo_u32 v167, v167, s25
	s_waitcnt vmcnt(24)
	ds_write_b128 v161, v[4:7]
	v_add3_u32 v161, s7, v163, v160
	v_and_b32_e32 v168, 0x70, v16
	ds_write_b128 v161, v[8:11]
	v_add3_u32 v161, s7, v165, v160
	v_add3_u32 v160, s7, v167, v160
	ds_write_b128 v161, v[12:15]
	ds_write_b128 v160, v[18:21]
	v_add_u32_e32 v160, s7, v168
	v_mad_u64_u32 v[162:163], s[0:1], v169, s63, v[160:161]
	ds_write_b128 v162, v[22:25] offset:17408
	v_mad_u64_u32 v[162:163], s[0:1], v170, s63, v[160:161]
	ds_write_b128 v162, v[26:29] offset:17408
	v_mad_u64_u32 v[162:163], s[0:1], v171, s63, v[160:161]
	ds_write_b128 v162, v[30:33] offset:26624
	v_mad_u64_u32 v[162:163], s[0:1], v172, s63, v[160:161]
	ds_write_b128 v162, v[34:37] offset:26624
	v_mad_u64_u32 v[162:163], s[0:1], v164, s63, v[160:161]
	ds_write_b128 v162, v[38:41] offset:26624
	v_mad_u64_u32 v[162:163], s[0:1], v166, s63, v[160:161]
	ds_write_b128 v162, v[42:45] offset:26624
	v_mad_u64_u32 v[162:163], s[0:1], v173, s63, v[160:161]
	v_mad_u64_u32 v[160:161], s[0:1], v174, s63, v[160:161]
	s_movk_i32 s0, 0x60
	s_nop 0
	v_cmp_gt_i32_e32 vcc, s0, v159
	ds_write_b128 v162, v[58:61] offset:45056
	ds_write_b128 v160, v[62:65] offset:45056
	s_and_saveexec_b64 s[0:1], vcc
	v_add_u32_e32 v16, s7, v16
	ds_write_b128 v16, v[0:3] offset:63488
	s_or_b64 exec, exec, s[0:1]
	s_cmp_gt_u32 s6, 59
	s_cselect_b64 s[0:1], -1, 0
	s_and_b64 vcc, exec, s[0:1]
	s_cbranch_vccnz .LBB0_1026
	v_mov_b32_e32 v159, v158
	s_add_u32 s4, s82, s9
	s_addc_u32 s5, s83, s8
	s_add_u32 s4, s4, 0x380000
	s_addc_u32 s5, s5, 0
	global_load_dwordx4 v[4:7], v200, s[4:5]
	global_load_dwordx4 v[8:11], v201, s[4:5]
	global_load_dwordx4 v[12:15], v202, s[4:5]
	global_load_dwordx4 v[18:21], v203, s[4:5]
	global_load_dwordx4 v[22:25], v204, s[4:5]
	global_load_dwordx4 v[26:29], v205, s[4:5]
	global_load_dwordx4 v[30:33], v206, s[4:5]
	global_load_dwordx4 v[34:37], v207, s[4:5]
	global_load_dwordx4 v[38:41], v208, s[4:5]
	global_load_dwordx4 v[42:45], v209, s[4:5]
	global_load_dwordx4 v[58:61], v210, s[4:5]
	global_load_dwordx4 v[62:65], v211, s[4:5]
	s_movk_i32 s4, 0x60
	v_cmp_gt_i32_e32 vcc, s4, v159
	s_and_saveexec_b64 s[4:5], vcc
	s_cbranch_execz .LBB0_1025
	v_lshlrev_b32_e32 v0, 2, v159
	s_add_u32 s22, s82, s11
	v_ashrrev_i32_e32 v1, 31, v0
	s_addc_u32 s23, s83, s10
	v_lshl_add_u64 v[0:1], v[0:1], 2, s[22:23]
	v_add_co_u32_e32 v0, vcc, 0x1f641000, v0
	s_nop 1
	v_addc_co_u32_e32 v1, vcc, 0, v1, vcc
	global_load_dwordx4 v[0:3], v[0:1], off offset:2048

.Lhl_b_w24:
	s_waitcnt vmcnt(24)
	s_mov_b32 s4, 0xffffffe
	v_add_u32_e32 v162, 0x100, v159
	v_add_u32_e32 v164, 0x200, v159
	v_add_u32_e32 v166, 0x300, v159
	v_ashrrev_i32_e32 v169, 3, v159
	v_ashrrev_i32_e32 v170, 3, v162
	v_lshrrev_b32_e32 v163, 4, v162
	v_lshrrev_b32_e32 v165, 4, v164
	v_lshrrev_b32_e32 v167, 4, v166
	v_bfe_u32 v162, v159, 3, 1
	v_lshrrev_b32_e32 v164, 3, v164
	v_lshrrev_b32_e32 v166, 3, v166
	v_add_u32_e32 v173, s2, v169
	v_add_u32_e32 v174, s2, v170
	s_bitcmp1_b32 s6, 0
	v_lshlrev_b32_e32 v16, 4, v159
	v_lshrrev_b32_e32 v161, 4, v159
	v_and_or_b32 v171, v169, s4, v162
	v_and_or_b32 v172, v170, s4, v162
	v_and_or_b32 v164, v164, s4, v162
	v_and_or_b32 v166, v166, s4, v162
	v_and_or_b32 v173, v173, s4, v162
	v_and_or_b32 v174, v174, s4, v162
	s_cselect_b32 s4, 0x10400, 0
	v_and_b32_e32 v160, 0xf0, v16
	v_mul_lo_u32 v161, v161, s25
	s_add_i32 s21, s4, 0
	v_mul_lo_u32 v163, v163, s25
	v_add3_u32 v161, s21, v161, v160
	v_mul_lo_u32 v165, v165, s25
	v_mul_lo_u32 v167, v167, s25
	ds_write_b128 v161, v[46:49]
	v_add3_u32 v161, s21, v163, v160
	v_and_b32_e32 v168, 0x70, v16
	ds_write_b128 v161, v[50:53]
	v_add3_u32 v161, s21, v165, v160
	v_add3_u32 v160, s21, v167, v160
	ds_write_b128 v161, v[66:69]
	ds_write_b128 v160, v[70:73]
	v_add_u32_e32 v160, s21, v168
	v_mad_u64_u32 v[162:163], s[4:5], v169, s63, v[160:161]
	ds_write_b128 v162, v[74:77] offset:17408
	v_mad_u64_u32 v[162:163], s[4:5], v170, s63, v[160:161]
	ds_write_b128 v162, v[78:81] offset:17408
	v_mad_u64_u32 v[162:163], s[4:5], v171, s63, v[160:161]
	ds_write_b128 v162, v[82:85] offset:26624
	v_mad_u64_u32 v[162:163], s[4:5], v172, s63, v[160:161]
	ds_write_b128 v162, v[86:89] offset:26624
	v_mad_u64_u32 v[162:163], s[4:5], v164, s63, v[160:161]
	ds_write_b128 v162, v[90:93] offset:26624
	v_mad_u64_u32 v[162:163], s[4:5], v166, s63, v[160:161]
	ds_write_b128 v162, v[94:97] offset:26624
	v_mad_u64_u32 v[162:163], s[4:5], v173, s63, v[160:161]
	v_mad_u64_u32 v[160:161], s[4:5], v174, s63, v[160:161]
	s_movk_i32 s4, 0x60
	s_nop 0
	v_cmp_gt_i32_e32 vcc, s4, v159
	ds_write_b128 v162, v[110:113] offset:45056
	ds_write_b128 v160, v[118:121] offset:45056
	s_and_saveexec_b64 s[4:5], vcc
	v_add_u32_e32 v16, s21, v16
	ds_write_b128 v16, v[54:57] offset:63488
	s_or_b64 exec, exec, s[4:5]
	s_cmp_gt_u32 s6, 58
	s_cbranch_scc1 .LBB0_1032
	v_mov_b32_e32 v159, v158
	s_add_u32 s4, s82, s9
	s_addc_u32 s5, s83, s8
	s_add_u32 s4, s4, 0x460000
	s_addc_u32 s5, s5, 0
	global_load_dwordx4 v[46:49], v200, s[4:5]
	global_load_dwordx4 v[50:53], v201, s[4:5]
	global_load_dwordx4 v[66:69], v202, s[4:5]
	global_load_dwordx4 v[70:73], v203, s[4:5]
	global_load_dwordx4 v[74:77], v204, s[4:5]
	global_load_dwordx4 v[78:81], v205, s[4:5]
	global_load_dwordx4 v[82:85], v206, s[4:5]
	global_load_dwordx4 v[86:89], v207, s[4:5]
	global_load_dwordx4 v[90:93], v208, s[4:5]
	global_load_dwordx4 v[94:97], v209, s[4:5]
	global_load_dwordx4 v[110:113], v210, s[4:5]
	global_load_dwordx4 v[118:121], v211, s[4:5]
	s_movk_i32 s4, 0x60
	v_cmp_gt_i32_e32 vcc, s4, v159
	s_and_saveexec_b64 s[4:5], vcc
	s_cbranch_execz .LBB0_1031
	v_lshlrev_b32_e32 v54, 2, v159
	s_add_u32 s22, s82, s11
	v_ashrrev_i32_e32 v55, 31, v54
	s_addc_u32 s23, s83, s10
	v_lshl_add_u64 v[54:55], v[54:55], 2, s[22:23]
	v_add_co_u32_e32 v54, vcc, 0x1f641000, v54
	s_nop 1
	v_addc_co_u32_e32 v55, vcc, 0, v55, vcc
	global_load_dwordx4 v[54:57], v[54:55], off offset:3584

.Lhl_c_w24:
	s_waitcnt vmcnt(24)
	s_mov_b32 s4, 0xffffffe
	v_lshlrev_b32_e32 v16, 4, v159
	v_lshrrev_b32_e32 v161, 4, v159
	v_add_u32_e32 v162, 0x100, v159
	v_and_b32_e32 v160, 0xf0, v16
	v_mul_lo_u32 v161, v161, s25
	v_lshrrev_b32_e32 v163, 4, v162
	v_add_u32_e32 v164, 0x200, v159
	v_add_u32_e32 v166, 0x300, v159
	v_mul_lo_u32 v163, v163, s25
	v_lshrrev_b32_e32 v165, 4, v164
	v_lshrrev_b32_e32 v167, 4, v166
	v_add3_u32 v161, s7, v161, v160
	v_mul_lo_u32 v165, v165, s25
	v_mul_lo_u32 v167, v167, s25
	ds_write_b128 v161, v[98:101]
	v_add3_u32 v161, s7, v163, v160
	v_and_b32_e32 v168, 0x70, v16
	v_ashrrev_i32_e32 v169, 3, v159
	v_ashrrev_i32_e32 v170, 3, v162
	ds_write_b128 v161, v[102:105]
	v_add3_u32 v161, s7, v165, v160
	v_add3_u32 v160, s7, v167, v160
	v_bfe_u32 v162, v159, 3, 1
	v_lshrrev_b32_e32 v164, 3, v164
	v_lshrrev_b32_e32 v166, 3, v166
	v_add_u32_e32 v173, s2, v169
	v_add_u32_e32 v174, s2, v170
	ds_write_b128 v161, v[114:117]
	ds_write_b128 v160, v[122:125]
	v_add_u32_e32 v160, s7, v168
	v_and_or_b32 v171, v169, s4, v162
	v_and_or_b32 v172, v170, s4, v162
	v_and_or_b32 v164, v164, s4, v162
	v_and_or_b32 v166, v166, s4, v162
	v_and_or_b32 v173, v173, s4, v162
	v_and_or_b32 v174, v174, s4, v162
	v_mad_u64_u32 v[162:163], s[4:5], v169, s63, v[160:161]
	ds_write_b128 v162, v[126:129] offset:17408
	v_mad_u64_u32 v[162:163], s[4:5], v170, s63, v[160:161]
	ds_write_b128 v162, v[130:133] offset:17408
	v_mad_u64_u32 v[162:163], s[4:5], v171, s63, v[160:161]
	ds_write_b128 v162, v[134:137] offset:26624
	v_mad_u64_u32 v[162:163], s[4:5], v172, s63, v[160:161]
	ds_write_b128 v162, v[138:141] offset:26624
	v_mad_u64_u32 v[162:163], s[4:5], v164, s63, v[160:161]
	ds_write_b128 v162, v[142:145] offset:26624
	v_mad_u64_u32 v[162:163], s[4:5], v166, s63, v[160:161]
	ds_write_b128 v162, v[146:149] offset:26624
	v_mad_u64_u32 v[162:163], s[4:5], v173, s63, v[160:161]
	v_mad_u64_u32 v[160:161], s[4:5], v174, s63, v[160:161]
	s_movk_i32 s4, 0x60
	s_nop 0
	v_cmp_gt_i32_e32 vcc, s4, v159
	ds_write_b128 v162, v[150:153] offset:45056
	ds_write_b128 v160, v[154:157] offset:45056
	s_and_saveexec_b64 s[4:5], vcc
	v_add_u32_e32 v16, s7, v16
	ds_write_b128 v16, v[106:109] offset:63488
	s_or_b64 exec, exec, s[4:5]
	s_cmp_gt_u32 s6, 57
	s_cbranch_scc1 .LBB0_1019
	v_mov_b32_e32 v159, v158
	s_add_u32 s4, s82, s9
	s_addc_u32 s5, s83, s8
	s_add_u32 s4, s4, 0x540000
	s_addc_u32 s5, s5, 0
	global_load_dwordx4 v[98:101], v200, s[4:5]
	global_load_dwordx4 v[102:105], v201, s[4:5]
	global_load_dwordx4 v[114:117], v202, s[4:5]
	global_load_dwordx4 v[122:125], v203, s[4:5]
	global_load_dwordx4 v[126:129], v204, s[4:5]
	global_load_dwordx4 v[130:133], v205, s[4:5]
	global_load_dwordx4 v[134:137], v206, s[4:5]
	global_load_dwordx4 v[138:141], v207, s[4:5]
	global_load_dwordx4 v[142:145], v208, s[4:5]
	global_load_dwordx4 v[146:149], v209, s[4:5]
	global_load_dwordx4 v[150:153], v210, s[4:5]
	global_load_dwordx4 v[154:157], v211, s[4:5]
	s_movk_i32 s4, 0x60
	v_cmp_gt_i32_e32 vcc, s4, v159
	s_and_saveexec_b64 s[4:5], vcc
	s_cbranch_execz .LBB0_1018
	v_lshlrev_b32_e32 v106, 2, v159
	s_add_u32 s22, s82, s11
	v_ashrrev_i32_e32 v107, 31, v106
	s_addc_u32 s23, s83, s10
	v_lshl_add_u64 v[106:107], v[106:107], 2, s[22:23]
	v_add_co_u32_e32 v106, vcc, 0x1f642000, v106
	s_nop 1
	v_addc_co_u32_e32 v107, vcc, 0, v107, vcc
	global_load_dwordx4 v[106:109], v[106:107], off offset:1024
	s_branch .LBB0_1018
